# as previous plus every 32-MFMA block of the three K-loops starts on an 8-byte boundary (two s_nop 0 in load segments of the residual GEMM loop)
# baseline (speedup 1.0000x reference)
; #define PG8_STAGE(bufoff, gbase, voff) do { _Pragma("unroll") for (int _i = 0; _i < 2; ++_i) \
;         __builtin_amdgcn_global_load_lds((const unsigned*)((const char*)(gbase) + (voff)[_i]), (PG8_LAS unsigned*)(lds + (bufoff) + ldsw + _i * 8192), 16, 0, 0); } while (0)
; #define PG8_LDA(dst, b, h) do { _Pragma("unroll") for (int m = 0; m < 4; ++m) _Pragma("unroll") for (int k = 0; k < 2; ++k) dst[m][k] = *(const PG8_LAS bf16x8*)(lds + PG8_SA(b, h) + aoff + m * 2048 + k * 1024); } while (0)
; #define PG8_LDB(dst, b, h) do { _Pragma("unroll") for (int n = 0; n < 2; ++n) _Pragma("unroll") for (int k = 0; k < 2; ++k) dst[n][k] = *(const PG8_LAS bf16x8*)(lds + PG8_SB(b, h) + boff + n * 2048 + k * 1024); } while (0)
; #define PG8_MMA(ai, bj, At, Bt) do { __builtin_amdgcn_s_setprio(1); _Pragma("unroll") for (int m = 0; m < 4; ++m) _Pragma("unroll") for (int n = 0; n < 2; ++n) _Pragma("unroll") for (int k = 0; k < 2; ++k) \
;         acc[ai][bj][m][n] = __builtin_amdgcn_mfma_f32_16x16x32_bf16(Bt[n][k], At[m][k], acc[ai][bj][m][n], 0, 0, 0); __builtin_amdgcn_s_setprio(0); } while (0)
; #define PG8_WAIT_V(n) asm volatile("s_waitcnt vmcnt(" #n ")" ::: "memory")
; #define PG8_WAIT_L(n) asm volatile("s_waitcnt lgkmcnt(" #n ")" ::: "memory")
; template <class Epi, class Sched, bool ALIGN_EPI = false, bool SP2 = false>
; __device__ __forceinline__ void gemm_phase(PG8_LAS unsigned char* lds, const Gemm g, const Sched& S, const Epi& E, const int tid_in) {
;     ...
;             const bool last = (t == nt - 2);
;             const char* a1 = cA + (size_t)(t + 1) * kstep;
;             const char* a2 = last ? nA : cA + (size_t)(t + 2) * kstep; const char* b2 = last ? nB : cB + (size_t)(t + 2) * kstep;
;             const char* a3 = a2 + kstep; const char* b3 = b2 + kstep;
;             if (last && has_next) S.a_ready(nxt);
;             if constexpr (SP2) {
;             PG8_LDB(B0, 0, 0); PG8_LDB(B1, 0, 1); PG8_SCHED; PG8_LDA(At, 0, 0); PG8_STAGE(PG8_SA(1, 1), a1 + hstep, voffA);
;             PG8_WAIT_V(8); PG8_WAIT_L(0); PG8_BAR; PG8_MMA(0, 0, At, B0); PG8_MMA(0, 1, At, B1); PG8_BAR; PG8_SCHED;
;             PG8_LDA(At, 0, 1); PG8_STAGE(PG8_SB(0, 0), b2, voffB); PG8_STAGE(PG8_SB(0, 1), b2 + hstep, voffB); PG8_STAGE(PG8_SA(0, 0), a2, voffA);
;             PG8_WAIT_V(8); PG8_WAIT_L(0); PG8_BAR; PG8_MMA(1, 0, At, B0); PG8_MMA(1, 1, At, B1); PG8_BAR; PG8_SCHED;
.LBB0_177:
	s_add_i32 s51, s12, 2
	s_add_u32 s52, s10, 0x80
	s_addc_u32 s13, s11, 0
	s_add_i32 s54, 0, 0x10000
	s_cmp_eq_u32 s31, s12
	s_cselect_b32 s13, s1, s13
	s_cselect_b32 s12, s0, s52
	s_cselect_b32 s53, s45, s15
	s_cselect_b32 s52, s44, s14
	s_add_i32 s55, 0, 0x14000
	v_add_u32_e32 v138, s54, v247
	v_add_u32_e32 v154, s55, v247
	ds_read_b128 v[126:129], v138
	ds_read_b128 v[130:133], v138 offset:1024
	ds_read_b128 v[134:137], v138 offset:2048
	ds_read_b128 v[138:141], v138 offset:3072
	ds_read_b128 v[142:145], v154
	ds_read_b128 v[146:149], v154 offset:1024
	ds_read_b128 v[150:153], v154 offset:2048
	ds_read_b128 v[154:157], v154 offset:3072
	v_lshl_add_u64 v[214:215], s[10:11], 0, v[206:207]
	s_add_i32 m0, s18, 0xc000
	ds_read_b128 v[158:161], v249
	ds_read_b128 v[162:165], v249 offset:1024
	ds_read_b128 v[170:173], v249 offset:2048
	ds_read_b128 v[178:181], v249 offset:3072
	ds_read_b128 v[182:185], v249 offset:4096
	ds_read_b128 v[186:189], v249 offset:5120
	ds_read_b128 v[190:193], v249 offset:6144
	ds_read_b128 v[210:213], v249 offset:7168
	global_load_lds_dwordx4 v[214:215], off
	v_lshl_add_u64 v[214:215], s[10:11], 0, v[208:209]
	s_add_i32 m0, s18, 0xe000
	s_nop 0
	global_load_lds_dwordx4 v[214:215], off
	s_waitcnt vmcnt(8)
	s_waitcnt lgkmcnt(0)
	s_barrier
	v_mfma_f32_16x16x32_bf16 v[174:177], v[126:129], v[158:161], v[174:177]
	v_mfma_f32_16x16x32_bf16 v[174:177], v[130:133], v[162:165], v[174:177]
	v_mfma_f32_16x16x32_bf16 v[114:117], v[126:129], v[170:173], v[114:117]
	v_mfma_f32_16x16x32_bf16 v[114:117], v[130:133], v[178:181], v[114:117]
	v_mfma_f32_16x16x32_bf16 v[98:101], v[126:129], v[182:185], v[98:101]
	v_mfma_f32_16x16x32_bf16 v[98:101], v[130:133], v[186:189], v[98:101]
	v_mfma_f32_16x16x32_bf16 v[82:85], v[126:129], v[190:193], v[82:85]
	v_mfma_f32_16x16x32_bf16 v[82:85], v[130:133], v[210:213], v[82:85]
	v_mfma_f32_16x16x32_bf16 v[166:169], v[134:137], v[158:161], v[166:169]
	v_mfma_f32_16x16x32_bf16 v[166:169], v[138:141], v[162:165], v[166:169]
	v_mfma_f32_16x16x32_bf16 v[110:113], v[134:137], v[170:173], v[110:113]
	v_mfma_f32_16x16x32_bf16 v[110:113], v[138:141], v[178:181], v[110:113]
	v_mfma_f32_16x16x32_bf16 v[94:97], v[134:137], v[182:185], v[94:97]
	v_mfma_f32_16x16x32_bf16 v[94:97], v[138:141], v[186:189], v[94:97]
	v_mfma_f32_16x16x32_bf16 v[78:81], v[134:137], v[190:193], v[78:81]
	v_mfma_f32_16x16x32_bf16 v[78:81], v[138:141], v[210:213], v[78:81]
	v_mfma_f32_16x16x32_bf16 v[122:125], v[142:145], v[158:161], v[122:125]
	v_mfma_f32_16x16x32_bf16 v[122:125], v[146:149], v[162:165], v[122:125]
	v_mfma_f32_16x16x32_bf16 v[106:109], v[142:145], v[170:173], v[106:109]
	v_mfma_f32_16x16x32_bf16 v[106:109], v[146:149], v[178:181], v[106:109]
	v_mfma_f32_16x16x32_bf16 v[90:93], v[142:145], v[182:185], v[90:93]
	v_mfma_f32_16x16x32_bf16 v[90:93], v[146:149], v[186:189], v[90:93]
	v_mfma_f32_16x16x32_bf16 v[74:77], v[142:145], v[190:193], v[74:77]
	v_mfma_f32_16x16x32_bf16 v[74:77], v[146:149], v[210:213], v[74:77]
	v_mfma_f32_16x16x32_bf16 v[118:121], v[150:153], v[158:161], v[118:121]
	v_mfma_f32_16x16x32_bf16 v[118:121], v[154:157], v[162:165], v[118:121]
	v_mfma_f32_16x16x32_bf16 v[102:105], v[150:153], v[170:173], v[102:105]
	v_mfma_f32_16x16x32_bf16 v[102:105], v[154:157], v[178:181], v[102:105]
	v_mfma_f32_16x16x32_bf16 v[86:89], v[150:153], v[182:185], v[86:89]
	v_mfma_f32_16x16x32_bf16 v[86:89], v[154:157], v[186:189], v[86:89]
	v_mfma_f32_16x16x32_bf16 v[70:73], v[150:153], v[190:193], v[70:73]
	v_mfma_f32_16x16x32_bf16 v[70:73], v[154:157], v[210:213], v[70:73]
	s_barrier
	s_add_i32 s54, s54, s17
	v_lshl_add_u64 v[214:215], s[52:53], 0, v[202:203]
	s_mov_b32 m0, s54
	ds_read_b128 v[158:161], v249 offset:16384
	ds_read_b128 v[162:165], v249 offset:17408
	ds_read_b128 v[170:173], v249 offset:18432
	ds_read_b128 v[178:181], v249 offset:19456
	ds_read_b128 v[182:185], v249 offset:20480
	ds_read_b128 v[186:189], v249 offset:21504
	ds_read_b128 v[190:193], v249 offset:22528
	ds_read_b128 v[210:213], v249 offset:23552
	global_load_lds_dwordx4 v[214:215], off
	s_add_i32 m0, s54, 0x2000
	v_lshl_add_u64 v[216:217], s[52:53], 0, v[198:199]
	s_add_u32 s52, s52, s62
	s_addc_u32 s53, s53, 0
	s_add_i32 s54, s55, s17
	global_load_lds_dwordx4 v[216:217], off
	v_lshl_add_u64 v[218:219], s[52:53], 0, v[202:203]
	s_mov_b32 m0, s54
	v_lshl_add_u64 v[220:221], s[52:53], 0, v[198:199]
	global_load_lds_dwordx4 v[218:219], off
	s_add_i32 m0, s54, 0x2000
	v_lshl_add_u64 v[222:223], s[12:13], 0, v[204:205]
	global_load_lds_dwordx4 v[220:221], off
	s_mov_b32 m0, s18
	v_lshl_add_u64 v[224:225], s[12:13], 0, v[200:201]
	global_load_lds_dwordx4 v[222:223], off
	s_mov_b32 m0, s19
	s_nop 0
	global_load_lds_dwordx4 v[224:225], off
	s_nop 0
	s_waitcnt vmcnt(8)
	s_waitcnt lgkmcnt(0)
	s_barrier
; #define PG8_STAGE(bufoff, gbase, voff) do { _Pragma("unroll") for (int _i = 0; _i < 2; ++_i) \
;         __builtin_amdgcn_global_load_lds((const unsigned*)((const char*)(gbase) + (voff)[_i]), (PG8_LAS unsigned*)(lds + (bufoff) + ldsw + _i * 8192), 16, 0, 0); } while (0)
; #define PG8_LDA(dst, b, h) do { _Pragma("unroll") for (int m = 0; m < 4; ++m) _Pragma("unroll") for (int k = 0; k < 2; ++k) dst[m][k] = *(const PG8_LAS bf16x8*)(lds + PG8_SA(b, h) + aoff + m * 2048 + k * 1024); } while (0)
; #define PG8_LDB(dst, b, h) do { _Pragma("unroll") for (int n = 0; n < 2; ++n) _Pragma("unroll") for (int k = 0; k < 2; ++k) dst[n][k] = *(const PG8_LAS bf16x8*)(lds + PG8_SB(b, h) + boff + n * 2048 + k * 1024); } while (0)
; #define PG8_MMA(ai, bj, At, Bt) do { __builtin_amdgcn_s_setprio(1); _Pragma("unroll") for (int m = 0; m < 4; ++m) _Pragma("unroll") for (int n = 0; n < 2; ++n) _Pragma("unroll") for (int k = 0; k < 2; ++k) \
;         acc[ai][bj][m][n] = __builtin_amdgcn_mfma_f32_16x16x32_bf16(Bt[n][k], At[m][k], acc[ai][bj][m][n], 0, 0, 0); __builtin_amdgcn_s_setprio(0); } while (0)
; #define PG8_WAIT_V(n) asm volatile("s_waitcnt vmcnt(" #n ")" ::: "memory")
; #define PG8_WAIT_L(n) asm volatile("s_waitcnt lgkmcnt(" #n ")" ::: "memory")
; #define PG8_BAR __builtin_amdgcn_s_barrier()
; #define PG8_SCHED __builtin_amdgcn_sched_barrier(0)
; template <class Epi, class Sched, bool ALIGN_EPI = false, bool SP2 = false>
; __device__ __forceinline__ void gemm_phase(PG8_LAS unsigned char* lds, const Gemm g, const Sched& S, const Epi& E, const int tid_in) {
;     ...
;             PG8_WAIT_V(8); PG8_WAIT_L(0); PG8_BAR; PG8_MMA(1, 0, At, B0); PG8_MMA(1, 1, At, B1); PG8_BAR; PG8_SCHED;
;             PG8_LDB(B0, 1, 0); PG8_LDB(B1, 1, 1); PG8_SCHED; PG8_LDA(At, 1, 0); PG8_STAGE(PG8_SA(0, 1), a2 + hstep, voffA);
;             PG8_WAIT_V(8); PG8_WAIT_L(0); PG8_BAR; PG8_MMA(0, 0, At, B0); PG8_MMA(0, 1, At, B1); PG8_BAR; PG8_SCHED;
	v_mfma_f32_16x16x32_bf16 v[66:69], v[126:129], v[158:161], v[66:69]
	v_mfma_f32_16x16x32_bf16 v[66:69], v[130:133], v[162:165], v[66:69]
	v_mfma_f32_16x16x32_bf16 v[50:53], v[126:129], v[170:173], v[50:53]
	v_mfma_f32_16x16x32_bf16 v[50:53], v[130:133], v[178:181], v[50:53]
	v_mfma_f32_16x16x32_bf16 v[34:37], v[126:129], v[182:185], v[34:37]
	v_mfma_f32_16x16x32_bf16 v[34:37], v[130:133], v[186:189], v[34:37]
	v_mfma_f32_16x16x32_bf16 v[18:21], v[126:129], v[190:193], v[18:21]
	v_mfma_f32_16x16x32_bf16 v[18:21], v[130:133], v[210:213], v[18:21]
	v_mfma_f32_16x16x32_bf16 v[62:65], v[134:137], v[158:161], v[62:65]
	v_mfma_f32_16x16x32_bf16 v[62:65], v[138:141], v[162:165], v[62:65]
	v_mfma_f32_16x16x32_bf16 v[46:49], v[134:137], v[170:173], v[46:49]
	v_mfma_f32_16x16x32_bf16 v[46:49], v[138:141], v[178:181], v[46:49]
	v_mfma_f32_16x16x32_bf16 v[30:33], v[134:137], v[182:185], v[30:33]
	v_mfma_f32_16x16x32_bf16 v[30:33], v[138:141], v[186:189], v[30:33]
	v_mfma_f32_16x16x32_bf16 v[14:17], v[134:137], v[190:193], v[14:17]
	v_mfma_f32_16x16x32_bf16 v[14:17], v[138:141], v[210:213], v[14:17]
	v_mfma_f32_16x16x32_bf16 v[58:61], v[142:145], v[158:161], v[58:61]
	v_mfma_f32_16x16x32_bf16 v[58:61], v[146:149], v[162:165], v[58:61]
	v_mfma_f32_16x16x32_bf16 v[42:45], v[142:145], v[170:173], v[42:45]
	v_mfma_f32_16x16x32_bf16 v[42:45], v[146:149], v[178:181], v[42:45]
	v_mfma_f32_16x16x32_bf16 v[26:29], v[142:145], v[182:185], v[26:29]
	v_mfma_f32_16x16x32_bf16 v[26:29], v[146:149], v[186:189], v[26:29]
	v_mfma_f32_16x16x32_bf16 v[10:13], v[142:145], v[190:193], v[10:13]
	v_mfma_f32_16x16x32_bf16 v[10:13], v[146:149], v[210:213], v[10:13]
	v_mfma_f32_16x16x32_bf16 v[54:57], v[150:153], v[158:161], v[54:57]
	v_mfma_f32_16x16x32_bf16 v[54:57], v[154:157], v[162:165], v[54:57]
	v_mfma_f32_16x16x32_bf16 v[38:41], v[150:153], v[170:173], v[38:41]
	v_mfma_f32_16x16x32_bf16 v[38:41], v[154:157], v[178:181], v[38:41]
	v_mfma_f32_16x16x32_bf16 v[22:25], v[150:153], v[182:185], v[22:25]
	v_mfma_f32_16x16x32_bf16 v[22:25], v[154:157], v[186:189], v[22:25]
	v_mfma_f32_16x16x32_bf16 v[6:9], v[150:153], v[190:193], v[6:9]
	v_mfma_f32_16x16x32_bf16 v[6:9], v[154:157], v[210:213], v[6:9]
	s_barrier
	s_add_i32 s52, 0, 0x18000
	s_add_i32 s53, 0, 0x1c000
	v_add_u32_e32 v138, s52, v247
	v_add_u32_e32 v154, s53, v247
	ds_read_b128 v[126:129], v138
	ds_read_b128 v[130:133], v138 offset:1024
	ds_read_b128 v[134:137], v138 offset:2048
	ds_read_b128 v[138:141], v138 offset:3072
	ds_read_b128 v[142:145], v154
	ds_read_b128 v[146:149], v154 offset:1024
	ds_read_b128 v[150:153], v154 offset:2048
	ds_read_b128 v[154:157], v154 offset:3072
	s_add_u32 s12, s12, s62
	s_addc_u32 s13, s13, 0
	s_mov_b32 m0, s22
	v_lshl_add_u64 v[226:227], s[12:13], 0, v[204:205]
	ds_read_b128 v[158:161], v249 offset:32768
	ds_read_b128 v[162:165], v249 offset:33792
	ds_read_b128 v[170:173], v249 offset:34816
	ds_read_b128 v[178:181], v249 offset:35840
	ds_read_b128 v[182:185], v249 offset:36864
	ds_read_b128 v[186:189], v249 offset:37888
	ds_read_b128 v[190:193], v249 offset:38912
	ds_read_b128 v[210:213], v249 offset:39936
	global_load_lds_dwordx4 v[226:227], off
	v_lshl_add_u64 v[226:227], s[12:13], 0, v[200:201]
	s_mov_b32 m0, s23
	s_nop 0
	global_load_lds_dwordx4 v[226:227], off
	s_nop 0
	s_waitcnt vmcnt(8)
	s_waitcnt lgkmcnt(0)
	s_barrier
	v_mfma_f32_16x16x32_bf16 v[174:177], v[126:129], v[158:161], v[174:177]
	v_mfma_f32_16x16x32_bf16 v[174:177], v[130:133], v[162:165], v[174:177]
	v_mfma_f32_16x16x32_bf16 v[114:117], v[126:129], v[170:173], v[114:117]
	v_mfma_f32_16x16x32_bf16 v[114:117], v[130:133], v[178:181], v[114:117]
	v_mfma_f32_16x16x32_bf16 v[98:101], v[126:129], v[182:185], v[98:101]
	v_mfma_f32_16x16x32_bf16 v[98:101], v[130:133], v[186:189], v[98:101]
	v_mfma_f32_16x16x32_bf16 v[82:85], v[126:129], v[190:193], v[82:85]
	v_mfma_f32_16x16x32_bf16 v[82:85], v[130:133], v[210:213], v[82:85]
	v_mfma_f32_16x16x32_bf16 v[166:169], v[134:137], v[158:161], v[166:169]
	v_mfma_f32_16x16x32_bf16 v[166:169], v[138:141], v[162:165], v[166:169]
	v_mfma_f32_16x16x32_bf16 v[110:113], v[134:137], v[170:173], v[110:113]
	v_mfma_f32_16x16x32_bf16 v[110:113], v[138:141], v[178:181], v[110:113]
	v_mfma_f32_16x16x32_bf16 v[94:97], v[134:137], v[182:185], v[94:97]
	v_mfma_f32_16x16x32_bf16 v[94:97], v[138:141], v[186:189], v[94:97]
	v_mfma_f32_16x16x32_bf16 v[78:81], v[134:137], v[190:193], v[78:81]
	v_mfma_f32_16x16x32_bf16 v[78:81], v[138:141], v[210:213], v[78:81]
	v_mfma_f32_16x16x32_bf16 v[122:125], v[142:145], v[158:161], v[122:125]
	v_mfma_f32_16x16x32_bf16 v[122:125], v[146:149], v[162:165], v[122:125]
	v_mfma_f32_16x16x32_bf16 v[106:109], v[142:145], v[170:173], v[106:109]
	v_mfma_f32_16x16x32_bf16 v[106:109], v[146:149], v[178:181], v[106:109]
	v_mfma_f32_16x16x32_bf16 v[90:93], v[142:145], v[182:185], v[90:93]
	v_mfma_f32_16x16x32_bf16 v[90:93], v[146:149], v[186:189], v[90:93]
	v_mfma_f32_16x16x32_bf16 v[74:77], v[142:145], v[190:193], v[74:77]
	v_mfma_f32_16x16x32_bf16 v[74:77], v[146:149], v[210:213], v[74:77]
	v_mfma_f32_16x16x32_bf16 v[118:121], v[150:153], v[158:161], v[118:121]
	v_mfma_f32_16x16x32_bf16 v[118:121], v[154:157], v[162:165], v[118:121]
	v_mfma_f32_16x16x32_bf16 v[102:105], v[150:153], v[170:173], v[102:105]
	v_mfma_f32_16x16x32_bf16 v[102:105], v[154:157], v[178:181], v[102:105]
	v_mfma_f32_16x16x32_bf16 v[86:89], v[150:153], v[182:185], v[86:89]
	v_mfma_f32_16x16x32_bf16 v[86:89], v[154:157], v[186:189], v[86:89]
	v_mfma_f32_16x16x32_bf16 v[70:73], v[150:153], v[190:193], v[70:73]
	v_mfma_f32_16x16x32_bf16 v[70:73], v[154:157], v[210:213], v[70:73]
	s_barrier
; #define PG8_STAGE(bufoff, gbase, voff) do { _Pragma("unroll") for (int _i = 0; _i < 2; ++_i) \
;         __builtin_amdgcn_global_load_lds((const unsigned*)((const char*)(gbase) + (voff)[_i]), (PG8_LAS unsigned*)(lds + (bufoff) + ldsw + _i * 8192), 16, 0, 0); } while (0)
; #define PG8_LDA(dst, b, h) do { _Pragma("unroll") for (int m = 0; m < 4; ++m) _Pragma("unroll") for (int k = 0; k < 2; ++k) dst[m][k] = *(const PG8_LAS bf16x8*)(lds + PG8_SA(b, h) + aoff + m * 2048 + k * 1024); } while (0)
; #define PG8_MMA(ai, bj, At, Bt) do { __builtin_amdgcn_s_setprio(1); _Pragma("unroll") for (int m = 0; m < 4; ++m) _Pragma("unroll") for (int n = 0; n < 2; ++n) _Pragma("unroll") for (int k = 0; k < 2; ++k) \
;         acc[ai][bj][m][n] = __builtin_amdgcn_mfma_f32_16x16x32_bf16(Bt[n][k], At[m][k], acc[ai][bj][m][n], 0, 0, 0); __builtin_amdgcn_s_setprio(0); } while (0)
; #define PG8_WAIT_V(n) asm volatile("s_waitcnt vmcnt(" #n ")" ::: "memory")
; #define PG8_WAIT_L(n) asm volatile("s_waitcnt lgkmcnt(" #n ")" ::: "memory")
; #define PG8_BAR __builtin_amdgcn_s_barrier()
; #define PG8_SCHED __builtin_amdgcn_sched_barrier(0)
; template <class Epi, class Sched, bool ALIGN_EPI = false, bool SP2 = false>
; __device__ __forceinline__ void gemm_phase(PG8_LAS unsigned char* lds, const Gemm g, const Sched& S, const Epi& E, const int tid_in) {
;     ...
;             PG8_LDA(At, 1, 1); PG8_STAGE(PG8_SB(1, 0), b3, voffB); PG8_STAGE(PG8_SB(1, 1), b3 + hstep, voffB); PG8_STAGE(PG8_SA(1, 0), a3, voffA);
;             PG8_WAIT_V(8); PG8_WAIT_L(0); PG8_BAR; PG8_MMA(1, 0, At, B0); PG8_MMA(1, 1, At, B1); PG8_BAR; PG8_SCHED;
;     ...
;         if constexpr (ALIGN_EPI) { if (wr == 0) PG8_BAR; }
	s_add_i32 s12, s52, s17
	v_lshl_add_u64 v[214:215], v[214:215], 0, s[28:29]
	s_mov_b32 m0, s12
	ds_read_b128 v[158:161], v249 offset:49152
	ds_read_b128 v[162:165], v249 offset:50176
	ds_read_b128 v[170:173], v249 offset:51200
	ds_read_b128 v[178:181], v249 offset:52224
	ds_read_b128 v[182:185], v249 offset:53248
	ds_read_b128 v[186:189], v249 offset:54272
	ds_read_b128 v[190:193], v249 offset:55296
	ds_read_b128 v[210:213], v249 offset:56320
	global_load_lds_dwordx4 v[214:215], off
	v_lshl_add_u64 v[214:215], v[216:217], 0, s[28:29]
	s_add_i32 m0, s12, 0x2000
	s_add_i32 s12, s53, s17
	global_load_lds_dwordx4 v[214:215], off
	v_lshl_add_u64 v[214:215], v[218:219], 0, s[28:29]
	s_mov_b32 m0, s12
	s_nop 0
	global_load_lds_dwordx4 v[214:215], off
	v_lshl_add_u64 v[214:215], v[220:221], 0, s[28:29]
	s_add_i32 m0, s12, 0x2000
	s_nop 0
	global_load_lds_dwordx4 v[214:215], off
	v_lshl_add_u64 v[214:215], v[222:223], 0, s[28:29]
	s_mov_b32 m0, s26
	s_nop 0
	global_load_lds_dwordx4 v[214:215], off
	v_lshl_add_u64 v[214:215], v[224:225], 0, s[28:29]
	s_mov_b32 m0, s27
	s_nop 0
	global_load_lds_dwordx4 v[214:215], off
	s_waitcnt vmcnt(8)
	s_waitcnt lgkmcnt(0)
	s_barrier
	v_mfma_f32_16x16x32_bf16 v[66:69], v[126:129], v[158:161], v[66:69]
	v_mfma_f32_16x16x32_bf16 v[66:69], v[130:133], v[162:165], v[66:69]
	v_mfma_f32_16x16x32_bf16 v[50:53], v[126:129], v[170:173], v[50:53]
	v_mfma_f32_16x16x32_bf16 v[50:53], v[130:133], v[178:181], v[50:53]
	v_mfma_f32_16x16x32_bf16 v[34:37], v[126:129], v[182:185], v[34:37]
	v_mfma_f32_16x16x32_bf16 v[34:37], v[130:133], v[186:189], v[34:37]
	v_mfma_f32_16x16x32_bf16 v[18:21], v[126:129], v[190:193], v[18:21]
	v_mfma_f32_16x16x32_bf16 v[18:21], v[130:133], v[210:213], v[18:21]
	v_mfma_f32_16x16x32_bf16 v[62:65], v[134:137], v[158:161], v[62:65]
	v_mfma_f32_16x16x32_bf16 v[62:65], v[138:141], v[162:165], v[62:65]
	v_mfma_f32_16x16x32_bf16 v[46:49], v[134:137], v[170:173], v[46:49]
	v_mfma_f32_16x16x32_bf16 v[46:49], v[138:141], v[178:181], v[46:49]
	v_mfma_f32_16x16x32_bf16 v[30:33], v[134:137], v[182:185], v[30:33]
	v_mfma_f32_16x16x32_bf16 v[30:33], v[138:141], v[186:189], v[30:33]
	v_mfma_f32_16x16x32_bf16 v[14:17], v[134:137], v[190:193], v[14:17]
	v_mfma_f32_16x16x32_bf16 v[14:17], v[138:141], v[210:213], v[14:17]
	v_mfma_f32_16x16x32_bf16 v[58:61], v[142:145], v[158:161], v[58:61]
	v_mfma_f32_16x16x32_bf16 v[58:61], v[146:149], v[162:165], v[58:61]
	v_mfma_f32_16x16x32_bf16 v[42:45], v[142:145], v[170:173], v[42:45]
	v_mfma_f32_16x16x32_bf16 v[42:45], v[146:149], v[178:181], v[42:45]
	v_mfma_f32_16x16x32_bf16 v[26:29], v[142:145], v[182:185], v[26:29]
	v_mfma_f32_16x16x32_bf16 v[26:29], v[146:149], v[186:189], v[26:29]
	v_mfma_f32_16x16x32_bf16 v[10:13], v[142:145], v[190:193], v[10:13]
	v_mfma_f32_16x16x32_bf16 v[10:13], v[146:149], v[210:213], v[10:13]
	v_mfma_f32_16x16x32_bf16 v[54:57], v[150:153], v[158:161], v[54:57]
	v_mfma_f32_16x16x32_bf16 v[54:57], v[154:157], v[162:165], v[54:57]
	v_mfma_f32_16x16x32_bf16 v[38:41], v[150:153], v[170:173], v[38:41]
	v_mfma_f32_16x16x32_bf16 v[38:41], v[154:157], v[178:181], v[38:41]
	v_mfma_f32_16x16x32_bf16 v[22:25], v[150:153], v[182:185], v[22:25]
	v_mfma_f32_16x16x32_bf16 v[22:25], v[154:157], v[186:189], v[22:25]
	v_mfma_f32_16x16x32_bf16 v[6:9], v[150:153], v[190:193], v[6:9]
	v_mfma_f32_16x16x32_bf16 v[6:9], v[154:157], v[210:213], v[6:9]
	s_barrier
	s_add_u32 s10, s10, 0x100
	s_addc_u32 s11, s11, 0
	s_add_u32 s14, s14, 0x100
	s_addc_u32 s15, s15, 0
	s_cmp_ge_u32 s51, s30
	s_mov_b32 s12, s51
	s_cbranch_scc0 .LBB0_177
	s_and_b64 vcc, exec, s[42:43]
	s_cbranch_vccz .LBB0_180
	s_barrier
